# v18 plus generic fallback of the slack copy for grids other than 256 workgroups (same code path on this chip)
# baseline (speedup 1.0000x reference)
.LBB0_1094:
	s_mov_b64 exec, -1
	v_readlane_b32 s44, v251, 4
	v_readlane_b32 s45, v254, 42
	v_lshrrev_b32_e32 v4, 6, v178
	s_lshr_b32 s45, s45, 3
	v_readfirstlane_b32 s46, v4
	s_cmp_ge_i32 s44, 11
	s_cselect_b32 s47, 1, 0
	s_mul_i32 s48, s47, 10
	s_sub_i32 s48, s44, s48
	s_lshl_b32 s49, s47, 12
	s_and_b32 s54, s45, 1
	s_cmp_eq_u32 s54, s47
	s_cselect_b32 s54, 1, 0
	s_mov_b32 s50, 1
	s_mov_b32 s52, 0
	s_movk_i32 s53, 0x1000
	v_readlane_b32 s55, v251, 8
	s_cmp_lg_u32 s55, 0
	s_cbranch_scc1 .Lsc_std
	s_cmp_lg_u32 s44, 20
	s_cbranch_scc1 .Lsc_done
	s_mov_b32 s49, 0
	s_lshl_b32 s51, s45, 3
	s_movk_i32 s50, 0x2000
	s_mov_b32 s52, s6
	s_movk_i32 s53, 0x2000
	s_branch .Lsc_go
.Lsc_std:
	s_cmp_eq_u32 s48, 1
	s_cbranch_scc1 .Lsc_g1
	s_cmp_eq_u32 s48, 5
	s_cbranch_scc1 .Lsc_g2
	s_cmp_eq_u32 s48, 6
	s_cbranch_scc1 .Lsc_g3
	s_cmp_eq_u32 s48, 8
	s_cbranch_scc1 .Lsc_g4
	s_cmp_eq_u32 s48, 9
	s_cbranch_scc1 .Lsc_g5
	s_branch .Lsc_done

.Lsc_loop:
	s_cmp_ge_u32 s51, s53
	s_cbranch_scc1 .Lsc_done
	s_add_i32 s60, s49, s51
	s_lshr_b32 s61, s60, 7
	s_lshl_b32 s61, s61, 22
	s_and_b32 s62, s60, 127
	s_lshl_b32 s62, s62, 15
	s_add_u32 s61, s61, s62
	s_add_u32 s62, s56, s61
	s_addc_u32 s63, s57, 0
	s_add_u32 s64, s58, s61
	s_addc_u32 s65, s59, 0
	global_load_dwordx4 v[8:11], v4, s[62:63] nt
	global_load_dwordx4 v[12:15], v4, s[62:63] offset:1024 nt
	global_load_dwordx4 v[16:19], v4, s[62:63] offset:2048 nt
	global_load_dwordx4 v[20:23], v4, s[62:63] offset:3072 nt
	global_load_dwordx4 v[24:27], v5, s[62:63] nt
	global_load_dwordx4 v[28:31], v5, s[62:63] offset:1024 nt
	global_load_dwordx4 v[32:35], v5, s[62:63] offset:2048 nt
	global_load_dwordx4 v[36:39], v5, s[62:63] offset:3072 nt
	global_load_dwordx4 v[40:43], v6, s[62:63] nt
	global_load_dwordx4 v[44:47], v6, s[62:63] offset:1024 nt
	global_load_dwordx4 v[48:51], v6, s[62:63] offset:2048 nt
	global_load_dwordx4 v[52:55], v6, s[62:63] offset:3072 nt
	global_load_dwordx4 v[56:59], v7, s[62:63] nt
	global_load_dwordx4 v[60:63], v7, s[62:63] offset:1024 nt
	global_load_dwordx4 v[64:67], v7, s[62:63] offset:2048 nt
	global_load_dwordx4 v[68:71], v7, s[62:63] offset:3072 nt
	s_waitcnt vmcnt(15)
	global_store_dwordx4 v4, v[8:11], s[64:65] nt
	s_waitcnt vmcnt(15)
	global_store_dwordx4 v4, v[12:15], s[64:65] offset:1024 nt
	s_waitcnt vmcnt(15)
	global_store_dwordx4 v4, v[16:19], s[64:65] offset:2048 nt
	s_waitcnt vmcnt(15)
	global_store_dwordx4 v4, v[20:23], s[64:65] offset:3072 nt
	s_waitcnt vmcnt(15)
	global_store_dwordx4 v5, v[24:27], s[64:65] nt
	s_waitcnt vmcnt(15)
	global_store_dwordx4 v5, v[28:31], s[64:65] offset:1024 nt
	s_waitcnt vmcnt(15)
	global_store_dwordx4 v5, v[32:35], s[64:65] offset:2048 nt
	s_waitcnt vmcnt(15)
	global_store_dwordx4 v5, v[36:39], s[64:65] offset:3072 nt
	s_waitcnt vmcnt(15)
	global_store_dwordx4 v6, v[40:43], s[64:65] nt
	s_waitcnt vmcnt(15)
	global_store_dwordx4 v6, v[44:47], s[64:65] offset:1024 nt
	s_waitcnt vmcnt(15)
	global_store_dwordx4 v6, v[48:51], s[64:65] offset:2048 nt
	s_waitcnt vmcnt(15)
	global_store_dwordx4 v6, v[52:55], s[64:65] offset:3072 nt
	s_waitcnt vmcnt(15)
	global_store_dwordx4 v7, v[56:59], s[64:65] nt
	s_waitcnt vmcnt(15)
	global_store_dwordx4 v7, v[60:63], s[64:65] offset:1024 nt
	s_waitcnt vmcnt(15)
	global_store_dwordx4 v7, v[64:67], s[64:65] offset:2048 nt
	s_waitcnt vmcnt(15)
	global_store_dwordx4 v7, v[68:71], s[64:65] offset:3072 nt
	s_add_i32 s51, s51, s52
	s_add_i32 s50, s50, -1
	s_cmp_lg_u32 s50, 0
	s_cbranch_scc1 .Lsc_loop
